# P6->P7 barrier: workgroups 128-255 (retention/sample role, no consumer of the LoRA phase) arrive but do not wait
# speedup vs baseline: 1.0023x; 1.0023x over previous
; __device__ __forceinline__ unsigned xb_ld(unsigned* p)              { return __hip_atomic_load(p, __ATOMIC_RELAXED, __HIP_MEMORY_SCOPE_AGENT); }
; __device__ __forceinline__ unsigned xb_add(unsigned* p, unsigned v) { return __hip_atomic_fetch_add(p, v, __ATOMIC_RELAXED, __HIP_MEMORY_SCOPE_AGENT); }
; #define XB_SPIN(cond, bar) do { unsigned _sp = 0; while (cond) { \
;     if ((++_sp & 255u) == 0u) { if (xb_ld(&(bar)[XB_TMO])) break; if (_sp > XB_SPIN_CAP) { atomicAdd(&(bar)[XB_TMO], 1u); break; } } } } while (0)
; __device__ __forceinline__ void xcd_barrier(unsigned* barw, volatile LAS unsigned* stw, const int wv) {
;     ...
;         const unsigned old = xb_add(&bar[XB_XSUB(b.x)], 1u);
;         const unsigned gen = old / nloc;
;         if (old + 1u == (gen + 1u) * nloc) {
;             __builtin_amdgcn_fence(__ATOMIC_RELEASE, "agent");
;             asm volatile("s_waitcnt vmcnt(0)" ::: "memory");
;             const unsigned og = xb_add(&bar[XB_TOP], 1u);
;             const unsigned tg = og / nx;
;             if (og + 1u == (tg + 1u) * nx) xb_add(&bar[XB_TOPGEN], 1u);
;             else XB_SPIN(xb_ld(&bar[XB_TOPGEN]) == tg, bar);
;             __builtin_amdgcn_fence(__ATOMIC_ACQUIRE, "agent");
.LBB0_555:
	s_or_b64 exec, exec, s[18:19]
	v_cvt_f32_u32_e32 v4, v2
	s_waitcnt vmcnt(0)
	v_readfirstlane_b32 s4, v3
	v_sub_u32_e32 v3, 0, v2
	v_rcp_iflag_f32_e32 v4, v4
	v_add_u32_e32 v5, s4, v1
	v_mul_f32_e32 v4, 0x4f7ffffe, v4
	v_cvt_u32_f32_e32 v4, v4
	v_mul_lo_u32 v1, v3, v4
	v_mul_hi_u32 v1, v4, v1
	v_add_u32_e32 v1, v4, v1
	v_mul_hi_u32 v1, v5, v1
	v_mul_lo_u32 v3, v1, v2
	v_sub_u32_e32 v3, v5, v3
	v_add_u32_e32 v4, 1, v1
	v_cmp_ge_u32_e32 vcc, v3, v2
	s_nop 1
	v_cndmask_b32_e32 v1, v1, v4, vcc
	v_sub_u32_e32 v4, v3, v2
	v_cndmask_b32_e32 v3, v3, v4, vcc
	v_add_u32_e32 v4, 1, v1
	v_cmp_ge_u32_e32 vcc, v3, v2
	v_add_u32_e32 v3, 1, v5
	s_nop 0
	v_cndmask_b32_e32 v1, v1, v4, vcc
	v_mul_lo_u32 v4, v2, v1
	v_add_u32_e32 v2, v4, v2
	v_cmp_ne_u32_e32 vcc, v3, v2
	s_and_saveexec_b64 s[4:5], vcc
	s_xor_b64 s[16:17], exec, s[4:5]
	s_cbranch_execz .LBB0_569
	s_waitcnt lgkmcnt(0)
	buffer_inv sc1
	v_mov_b32_e32 v0, 0x3100
	global_load_dword v0, v0, s[10:11] offset:1024 sc1
	s_add_u32 s20, s10, 0x3500
	s_addc_u32 s21, s11, 0
	s_waitcnt vmcnt(0)
	v_cmp_eq_u32_e32 vcc, v0, v1
	s_cmp_lt_u32 s2, 0x80
	s_cselect_b64 s[98:99], -1, 0
	s_and_b64 vcc, vcc, s[98:99]
	s_and_saveexec_b64 s[18:19], vcc
	s_cbranch_execz .LBB0_568
	s_mov_b32 s4, 1
	s_mov_b64 s[22:23], 0
	v_mov_b32_e32 v0, 0
	s_branch .LBB0_559

; __device__ __forceinline__ unsigned xb_ld(unsigned* p)              { return __hip_atomic_load(p, __ATOMIC_RELAXED, __HIP_MEMORY_SCOPE_AGENT); }
; __device__ __forceinline__ unsigned xb_add(unsigned* p, unsigned v) { return __hip_atomic_fetch_add(p, v, __ATOMIC_RELAXED, __HIP_MEMORY_SCOPE_AGENT); }
; #define XB_SPIN(cond, bar) do { unsigned _sp = 0; while (cond) { \
;     if ((++_sp & 255u) == 0u) { if (xb_ld(&(bar)[XB_TMO])) break; if (_sp > XB_SPIN_CAP) { atomicAdd(&(bar)[XB_TMO], 1u); break; } } } } while (0)
; __device__ __forceinline__ void xcd_barrier(unsigned* barw, volatile LAS unsigned* stw, const int wv) {
;     ...
;         const unsigned old = xb_add(&bar[XB_XSUB(b.x)], 1u);
;         const unsigned gen = old / nloc;
;         if (old + 1u == (gen + 1u) * nloc) {
;             __builtin_amdgcn_fence(__ATOMIC_RELEASE, "agent");
;             asm volatile("s_waitcnt vmcnt(0)" ::: "memory");
;             const unsigned og = xb_add(&bar[XB_TOP], 1u);
;             const unsigned tg = og / nx;
;             if (og + 1u == (tg + 1u) * nx) xb_add(&bar[XB_TOPGEN], 1u);
;             else XB_SPIN(xb_ld(&bar[XB_TOPGEN]) == tg, bar);
;             __builtin_amdgcn_fence(__ATOMIC_ACQUIRE, "agent");
.LBB0_572:
	s_or_b64 exec, exec, s[18:19]
	v_cvt_f32_u32_e32 v3, v0
	s_waitcnt vmcnt(0)
	v_readfirstlane_b32 s4, v2
	s_add_u32 s10, s10, 0x3500
	s_addc_u32 s11, s11, 0
	v_rcp_iflag_f32_e32 v3, v3
	v_add_u32_e32 v1, s4, v1
	s_mov_b64 s[18:19], -1
	v_mul_f32_e32 v2, 0x4f7ffffe, v3
	v_cvt_u32_f32_e32 v2, v2
	v_sub_u32_e32 v3, 0, v0
	v_mul_lo_u32 v3, v3, v2
	v_mul_hi_u32 v3, v2, v3
	v_add_u32_e32 v2, v2, v3
	v_mul_hi_u32 v2, v1, v2
	v_mul_lo_u32 v3, v2, v0
	v_sub_u32_e32 v3, v1, v3
	v_add_u32_e32 v4, 1, v2
	v_cmp_ge_u32_e32 vcc, v3, v0
	v_add_u32_e32 v1, 1, v1
	s_nop 0
	v_cndmask_b32_e32 v2, v2, v4, vcc
	v_sub_u32_e32 v4, v3, v0
	v_cndmask_b32_e32 v3, v3, v4, vcc
	v_add_u32_e32 v4, 1, v2
	v_cmp_ge_u32_e32 vcc, v3, v0
	s_nop 1
	v_cndmask_b32_e32 v2, v2, v4, vcc
	v_mul_lo_u32 v3, v0, v2
	v_add_u32_e32 v0, v3, v0
	v_cmp_ne_u32_e32 vcc, v1, v0
	v_mov_b64_e32 v[0:1], s[10:11]
	s_and_saveexec_b64 s[16:17], vcc
	s_cbranch_execz .LBB0_584
	v_mov_b32_e32 v0, 0
	global_load_dword v1, v0, s[10:11] sc1
	s_mov_b64 s[20:21], 0
	s_waitcnt vmcnt(0)
	v_cmp_eq_u32_e32 vcc, v1, v2
	s_cmp_lt_u32 s2, 0x80
	s_cselect_b64 s[98:99], -1, 0
	s_and_b64 vcc, vcc, s[98:99]
	s_and_saveexec_b64 s[18:19], vcc
	s_cbranch_execz .LBB0_583
	s_mov_b32 s4, 1
	s_branch .LBB0_576
